# MLA KN LDS-DMA pieces also use SGPR base + 32-bit VGPR offset (SALU base advance)
# speedup vs baseline: 1.0049x; 1.0023x over previous
;   DI void init_offs() {
; #pragma unroll
;     for (int q = 0; q < NKL; ++q) {
;       const int c = tid + 256 * q, row = c / KCH, cc = c % KCH;
;       koff[q] = (DQK == 96 && cc >= 8) ? row * 32 + (cc - 8) * 8 : row * kpitch + cc * 8;
;     }
; #pragma unroll
;     for (int q = 0; q < 2; ++q) { const int c = tid + 256 * q, dv = c >> 3, kc = c & 7; voff[q] = dv * MPAD + kc * 8; }
;   }
;   DI void gload_k(int t) {
;     const int row0 = rowk0 + t * 64;
;     const u16* kt = Kb + (size_t)row0 * kpitch;
;     const u16* pt = KPEb + (size_t)row0 * 32;
; #pragma unroll
;     for (int q = 0; q < NKL; ++q) {
;       const int c = tid + 256 * q, cc = c % KCH;
;       rk[q] = ldg16(((DQK == 96 && cc >= 8) ? pt : kt) + koff[q]);
;     }
;   }
;   DI void gload_v(int t) {
;     const u16* vt = Vt + (rowk0 + t * 64);
; #pragma unroll
;     for (int q = 0; q < 2; ++q) rv[q] = ldg16(vt + voff[q]);
;   }
;   DI void sstore_k(int buf) {
; #pragma unroll
;     for (int q = 0; q < NKL; ++q) {
;       const int c = tid + 256 * q, row = c / KCH, cc = c % KCH;
;       *(u32x4*)(sK + buf * KBUF + row * KP + cc * 8) = rk[q];
;     }
;   }
; template <int DQK>
; DI void attn_item(const u16* __restrict__ Qb, int qpitch, const u16* __restrict__ Kb, int kpitch, const u16* __restrict__ KPEb,
;                   const u16* __restrict__ Vt, float* __restrict__ ssq, int rowq0, int rowk0, int nt, char* smem, int tid, bool dry) {
;     ...
;   c.gload_k(0); c.gload_v(0);
;   __syncthreads();
;   c.sstore_k(0); c.sstore_v(0);
;   if (nt > 1) c.gload_k(1);
;   __syncthreads();
;   c.qk(0, sa);
.Lm_entry:
	v_mov_b32_e32 v181, 0
	v_mov_b32_e32 v182, 0
	v_mov_b32_e32 v183, 0
	v_mov_b32_e32 v238, 0
	v_mov_b32_e32 v239, 0
	s_waitcnt vmcnt(0)
	v_mov_b32_e32 v100, v245
	v_mul_u32_u24_e32 v101, 0xaaab, v100
	v_lshrrev_b32_e32 v101, 19, v101
	v_mul_u32_u24_e32 v102, 12, v101
	v_sub_u32_e32 v102, v100, v102
	v_bfe_u32 v103, v101, 1, 3
	v_xor_b32_e32 v103, v103, v102
	v_and_b32_e32 v103, 7, v103
	v_lshlrev_b32_e32 v103, 4, v103
	v_lshl_add_u32 v103, v101, 7, v103
	v_add_u32_e32 v103, 13312, v103
	v_bfe_u32 v104, v101, 2, 2
	v_xor_b32_e32 v104, v104, v102
	v_and_b32_e32 v104, 3, v104
	v_lshlrev_b32_e32 v104, 4, v104
	v_lshl_add_u32 v104, v101, 6, v104
	v_add_u32_e32 v104, 21504, v104
	v_cmp_gt_u32_e32 vcc, 8, v102
	s_nop 1
	v_cndmask_b32_e32 v103, v104, v103, vcc
	ds_write_b128 v103, v[160:163]
	v_add_u32_e32 v100, 256, v245
	v_mul_u32_u24_e32 v101, 0xaaab, v100
	v_lshrrev_b32_e32 v101, 19, v101
	v_mul_u32_u24_e32 v102, 12, v101
	v_sub_u32_e32 v102, v100, v102
	v_bfe_u32 v103, v101, 1, 3
	v_xor_b32_e32 v103, v103, v102
	v_and_b32_e32 v103, 7, v103
	v_lshlrev_b32_e32 v103, 4, v103
	v_lshl_add_u32 v103, v101, 7, v103
	v_add_u32_e32 v103, 13312, v103
	v_bfe_u32 v104, v101, 2, 2
	v_xor_b32_e32 v104, v104, v102
	v_and_b32_e32 v104, 3, v104
	v_lshlrev_b32_e32 v104, 4, v104
	v_lshl_add_u32 v104, v101, 6, v104
	v_add_u32_e32 v104, 21504, v104
	v_cmp_gt_u32_e32 vcc, 8, v102
	s_nop 1
	v_cndmask_b32_e32 v103, v104, v103, vcc
	ds_write_b128 v103, v[164:167]
	v_add_u32_e32 v100, 512, v245
	v_mul_u32_u24_e32 v101, 0xaaab, v100
	v_lshrrev_b32_e32 v101, 19, v101
	v_mul_u32_u24_e32 v102, 12, v101
	v_sub_u32_e32 v102, v100, v102
	v_bfe_u32 v103, v101, 1, 3
	v_xor_b32_e32 v103, v103, v102
	v_and_b32_e32 v103, 7, v103
	v_lshlrev_b32_e32 v103, 4, v103
	v_lshl_add_u32 v103, v101, 7, v103
	v_add_u32_e32 v103, 13312, v103
	v_bfe_u32 v104, v101, 2, 2
	v_xor_b32_e32 v104, v104, v102
	v_and_b32_e32 v104, 3, v104
	v_lshlrev_b32_e32 v104, 4, v104
	v_lshl_add_u32 v104, v101, 6, v104
	v_add_u32_e32 v104, 21504, v104
	v_cmp_gt_u32_e32 vcc, 8, v102
	s_nop 1
	v_cndmask_b32_e32 v103, v104, v103, vcc
	ds_write_b128 v103, v[168:171]
	v_lshrrev_b32_e32 v100, 3, v245
	v_and_b32_e32 v101, 7, v245
	v_bfe_u32 v102, v245, 4, 3
	v_xor_b32_e32 v101, v101, v102
	v_lshlrev_b32_e32 v101, 4, v101
	v_lshl_add_u32 v100, v100, 7, v101
	ds_write_b128 v100, v[172:175] offset:25600
	ds_write_b128 v100, v[176:179] offset:29696
	v_readfirstlane_b32 s45, v245
	s_nop 3
	s_lshr_b32 s45, s45, 6
	s_lshl_b32 s1, s45, 4
	v_lshrrev_b32_e32 v101, 3, v227
	v_lshrrev_b32_e32 v102, 4, v227
	v_and_b32_e32 v103, 7, v227
	v_xor_b32_e32 v103, v103, v102
	v_lshlrev_b32_e32 v103, 4, v103
	v_xor_b32_e32 v102, 64, v103
	v_add_u32_e32 v101, s1, v101
	v_lshl_add_u32 v104, v101, 10, v103
	v_lshl_add_u32 v106, v101, 10, v102
	v_add_u32_e32 v106, 0x1c00, v106
	v_mov_b32_e32 v105, 0
	v_mov_b32_e32 v107, 0
	v_mul_u32_u24_e32 v108, 0x20600, v101
	v_add_u32_e32 v110, v108, v102
	v_add_u32_e32 v108, v108, v103
	v_add_u32_e32 v110, 0x102c00, v110
	v_mov_b32_e32 v109, 0
	v_mov_b32_e32 v111, 0
	v_lshrrev_b32_e32 v112, 2, v227
	v_add_u32_e32 v112, s1, v112
	v_and_b32_e32 v113, 3, v227
	v_bfe_u32 v114, v227, 4, 2
	v_xor_b32_e32 v113, v113, v114
	v_lshlrev_b32_e32 v113, 4, v113
	v_lshl_add_u32 v112, v112, 6, v113
	v_mov_b32_e32 v113, 0
	s_sub_i32 s0, s44, 64
	s_ashr_i32 s1, s0, 31
	s_lshl_b64 s[20:21], s[0:1], 10
	s_lshl_b64 s[0:1], s[0:1], 6
	s_add_u32 s20, s26, s20
	s_addc_u32 s21, s27, s21
	s_add_u32 s0, s81, s0
	s_addc_u32 s1, s64, s1
	v_mov_b32_e32 v170, v104
	v_mov_b32_e32 v172, v106
	v_lshl_add_u64 v[174:175], v[112:113], 0, s[0:1]
	s_add_i32 s0, s44, 0xffffff80
	s_ashr_i32 s1, s0, 31
	s_lshl_b64 s[0:1], s[0:1], 1
	s_add_u32 s0, s35, s0
	s_addc_u32 s1, s30, s1
	v_lshl_add_u64 v[176:177], v[108:109], 0, s[0:1]
	v_lshl_add_u64 v[178:179], v[110:111], 0, s[0:1]
	s_lshl_b32 s44, s45, 11
	s_lshl_b32 s45, s45, 10
	v_and_b32_e32 v100, 31, v227
	v_lshrrev_b32_e32 v101, 5, v227
	v_and_b32_e32 v102, 0x13, v100
	v_and_b32_e32 v103, 4, v100
	v_lshl_or_b32 v102, v103, 1, v102
	v_and_b32_e32 v103, 8, v100
	v_lshrrev_b32_e32 v103, 1, v103
	v_or_b32_e32 v102, v102, v103
	v_bfe_u32 v103, v102, 1, 3
	v_bfe_u32 v104, v100, 1, 3
	v_bfe_u32 v107, v102, 2, 2
	v_or_b32_e32 v105, 0, v101
	v_xor_b32_e32 v106, v105, v103
	v_lshlrev_b32_e32 v106, 4, v106
	v_lshl_add_u32 v160, v102, 7, v106
	v_xor_b32_e32 v106, v105, v104
	v_lshlrev_b32_e32 v106, 4, v106
	v_lshl_add_u32 v166, v100, 7, v106
	v_or_b32_e32 v105, 2, v101
	v_xor_b32_e32 v106, v105, v103
	v_lshlrev_b32_e32 v106, 4, v106
	v_lshl_add_u32 v161, v102, 7, v106
	v_xor_b32_e32 v106, v105, v104
	v_lshlrev_b32_e32 v106, 4, v106
	v_lshl_add_u32 v167, v100, 7, v106
	v_or_b32_e32 v105, 4, v101
	v_xor_b32_e32 v106, v105, v103
	v_lshlrev_b32_e32 v106, 4, v106
	v_lshl_add_u32 v162, v102, 7, v106
	v_xor_b32_e32 v106, v105, v104
	v_lshlrev_b32_e32 v106, 4, v106
	v_lshl_add_u32 v168, v100, 7, v106
	v_or_b32_e32 v105, 6, v101
	v_xor_b32_e32 v106, v105, v103
	v_lshlrev_b32_e32 v106, 4, v106
	v_lshl_add_u32 v163, v102, 7, v106
	v_xor_b32_e32 v106, v105, v104
	v_lshlrev_b32_e32 v106, 4, v106
	v_lshl_add_u32 v169, v100, 7, v106
	v_or_b32_e32 v105, 0, v101
	v_xor_b32_e32 v106, v105, v107
	v_lshlrev_b32_e32 v106, 4, v106
	v_lshl_add_u32 v164, v102, 6, v106
	v_or_b32_e32 v105, 2, v101
	v_xor_b32_e32 v106, v105, v107
	v_lshlrev_b32_e32 v106, 4, v106
	v_lshl_add_u32 v165, v102, 6, v106
	s_waitcnt lgkmcnt(0)
	s_barrier
	s_add_i32 m0, s44, 0
	s_nop 0
	global_load_lds_dwordx4 v170, s[20:21]
	global_load_lds_dwordx4 v172, s[20:21] offset:1024
	s_add_i32 m0, s45, 8192
	s_nop 0
	global_load_lds_dwordx4 v[174:175], off
	s_add_u32 s20, s20, 0x10000
	s_addc_u32 s21, s21, 0
	s_mov_b64 s[0:1], 0x1000
	v_lshl_add_u64 v[174:175], v[174:175], 0, s[0:1]
	ds_read_b128 v[112:115], v162 offset:13312
	ds_read_b128 v[116:119], v162 offset:17408
	ds_read_b128 v[120:123], v163 offset:13312
	ds_read_b128 v[124:127], v163 offset:17408
	ds_read_b128 v[96:99], v160 offset:13312
	ds_read_b128 v[100:103], v160 offset:17408
	ds_read_b128 v[104:107], v161 offset:13312
	ds_read_b128 v[108:111], v161 offset:17408
	v_max3_f32 v240, v48, v32, v49
	v_max3_f32 v241, v33, v50, v34
	v_max3_f32 v240, v51, v35, v240
	v_max3_f32 v241, v52, v36, v241
	v_max3_f32 v240, v53, v37, v240
	v_max3_f32 v241, v54, v38, v241
	v_max3_f32 v240, v55, v39, v240
	v_max3_f32 v241, v56, v40, v241
	v_max3_f32 v240, v57, v41, v240
	v_max3_f32 v241, v58, v42, v241
	v_max3_f32 v240, v59, v43, v240
	v_max3_f32 v241, v60, v44, v241
	v_max3_f32 v240, v61, v45, v240
	v_max3_f32 v241, v62, v46, v241
	v_max3_f32 v240, v63, v47, v240
	v_max_f32_e32 v240, v240, v241
	v_and_b32_e32 v181, 0x7fff, v180
	v_cmp_ne_u32_e32 vcc, 0, v181
	v_mov_b32_e32 v181, 0
	s_cbranch_vccnz .LBB0_268

;   DI void gload_k(int t) {
;     const int row0 = rowk0 + t * 64;
;     const u16* kt = Kb + (size_t)row0 * kpitch;
;     const u16* pt = KPEb + (size_t)row0 * 32;
; #pragma unroll
;     for (int q = 0; q < NKL; ++q) {
;       const int c = tid + 256 * q, cc = c % KCH;
;       rk[q] = ldg16(((DQK == 96 && cc >= 8) ? pt : kt) + koff[q]);
;     }
;   }
;   template <int PAR>
;   DI void step(int t, f32x16 (&cur)[2], f32x16 (&nxt)[2]) {
;     ...
;     float psum = 0.f;
; #pragma unroll
;     for (int kb2 = 0; kb2 < 2; ++kb2)
; #pragma unroll
;       for (int i = 0; i < 16; ++i) { const float pv = __builtin_amdgcn_exp2f(cur[kb2][i]); cur[kb2][i] = pv; psum += pv; }
;     l += psum;
;     if (t + 2 < nt) gload_k(t + 2);
.Lmf_rareA_ret:
	v_exp_f32_e32 v48, v48
	v_exp_f32_e32 v49, v49
	v_exp_f32_e32 v50, v50
	v_add_f32_e32 v238, v48, v238
	v_exp_f32_e32 v51, v51
	v_add_f32_e32 v239, v49, v239
	v_exp_f32_e32 v52, v52
	v_add_f32_e32 v238, v50, v238
	s_waitcnt lgkmcnt(0)
	v_mfma_f32_32x32x16_bf16 v[80:95], v[96:99], v[136:139], 0
	ds_read_b128 v[96:99], v164 offset:21504
	v_exp_f32_e32 v53, v53
	v_add_f32_e32 v239, v51, v239
	v_exp_f32_e32 v54, v54
	v_add_f32_e32 v238, v52, v238
	v_exp_f32_e32 v55, v55
	v_mfma_f32_32x32x16_bf16 v[64:79], v[100:103], v[136:139], 0
	ds_read_b128 v[100:103], v164 offset:23552
	v_add_f32_e32 v239, v53, v239
	v_cvt_pk_bf16_f32 v48, v48, v49
	v_add_f32_e32 v238, v54, v238
	v_cvt_pk_bf16_f32 v49, v50, v51
	v_add_f32_e32 v239, v55, v239
	v_mfma_f32_32x32x16_bf16 v[80:95], v[104:107], v[140:143], v[80:95]
	ds_read_b128 v[104:107], v165 offset:21504
	v_cvt_pk_bf16_f32 v50, v52, v53
	v_cvt_pk_bf16_f32 v51, v54, v55
	v_exp_f32_e32 v56, v56
	v_exp_f32_e32 v57, v57
	v_exp_f32_e32 v58, v58
	v_mfma_f32_32x32x16_bf16 v[64:79], v[108:111], v[140:143], v[64:79]
	ds_read_b128 v[108:111], v165 offset:23552
	v_add_f32_e32 v238, v56, v238
	v_exp_f32_e32 v59, v59
	v_add_f32_e32 v239, v57, v239
	v_exp_f32_e32 v60, v60
	v_add_f32_e32 v238, v58, v238
	s_waitcnt vmcnt(0)
	s_waitcnt lgkmcnt(0)
	s_barrier
	s_add_i32 s0, s31, -1
	s_cmp_ge_u32 s0, s19
	s_cselect_b64 s[14:15], -1, 0
	s_cmp_ge_u32 s31, s19
	s_cbranch_scc1 .Lmf_skipKA
	s_add_i32 m0, s44, 13312
	s_nop 0
	global_load_lds_dwordx4 v170, s[20:21]
	global_load_lds_dwordx4 v172, s[20:21] offset:1024
	s_add_i32 m0, s45, 21504
	s_nop 0
	global_load_lds_dwordx4 v[174:175], off
	s_add_u32 s20, s20, 0x10000
	s_addc_u32 s21, s21, 0
	s_mov_b64 s[0:1], 0x1000
	v_lshl_add_u64 v[174:175], v[174:175], 0, s[0:1]

;   DI void gload_k(int t) {
;     const int row0 = rowk0 + t * 64;
;     const u16* kt = Kb + (size_t)row0 * kpitch;
;     const u16* pt = KPEb + (size_t)row0 * 32;
; #pragma unroll
;     for (int q = 0; q < NKL; ++q) {
;       const int c = tid + 256 * q, cc = c % KCH;
;       rk[q] = ldg16(((DQK == 96 && cc >= 8) ? pt : kt) + koff[q]);
;     }
;   }
;   template <int PAR>
;   DI void step(int t, f32x16 (&cur)[2], f32x16 (&nxt)[2]) {
;     ...
;     float psum = 0.f;
; #pragma unroll
;     for (int kb2 = 0; kb2 < 2; ++kb2)
; #pragma unroll
;       for (int i = 0; i < 16; ++i) { const float pv = __builtin_amdgcn_exp2f(cur[kb2][i]); cur[kb2][i] = pv; psum += pv; }
;     l += psum;
;     if (t + 2 < nt) gload_k(t + 2);
.Lmf_rareB_ret:
	v_exp_f32_e32 v80, v80
	v_exp_f32_e32 v81, v81
	v_exp_f32_e32 v82, v82
	v_add_f32_e32 v238, v80, v238
	v_exp_f32_e32 v83, v83
	v_add_f32_e32 v239, v81, v239
	v_exp_f32_e32 v84, v84
	v_add_f32_e32 v238, v82, v238
	s_waitcnt lgkmcnt(0)
	v_mfma_f32_32x32x16_bf16 v[48:63], v[96:99], v[136:139], 0
	ds_read_b128 v[96:99], v164 offset:8192
	v_exp_f32_e32 v85, v85
	v_add_f32_e32 v239, v83, v239
	v_exp_f32_e32 v86, v86
	v_add_f32_e32 v238, v84, v238
	v_exp_f32_e32 v87, v87
	v_mfma_f32_32x32x16_bf16 v[32:47], v[100:103], v[136:139], 0
	ds_read_b128 v[100:103], v164 offset:10240
	v_add_f32_e32 v239, v85, v239
	v_cvt_pk_bf16_f32 v80, v80, v81
	v_add_f32_e32 v238, v86, v238
	v_cvt_pk_bf16_f32 v81, v82, v83
	v_add_f32_e32 v239, v87, v239
	v_mfma_f32_32x32x16_bf16 v[48:63], v[104:107], v[140:143], v[48:63]
	ds_read_b128 v[104:107], v165 offset:8192
	v_cvt_pk_bf16_f32 v82, v84, v85
	v_cvt_pk_bf16_f32 v83, v86, v87
	v_exp_f32_e32 v88, v88
	v_exp_f32_e32 v89, v89
	v_exp_f32_e32 v90, v90
	v_mfma_f32_32x32x16_bf16 v[32:47], v[108:111], v[140:143], v[32:47]
	ds_read_b128 v[108:111], v165 offset:10240
	v_add_f32_e32 v238, v88, v238
	v_exp_f32_e32 v91, v91
	v_add_f32_e32 v239, v89, v239
	v_exp_f32_e32 v92, v92
	v_add_f32_e32 v238, v90, v238
	s_waitcnt vmcnt(0)
	s_waitcnt lgkmcnt(0)
	s_barrier
	s_add_i32 s0, s31, 1
	s_cmp_ge_u32 s0, s19
	s_cbranch_scc1 .Lmf_skipKB
	s_add_i32 m0, s44, 0
	s_nop 0
	global_load_lds_dwordx4 v170, s[20:21]
	global_load_lds_dwordx4 v172, s[20:21] offset:1024
	s_add_i32 m0, s45, 8192
	s_nop 0
	global_load_lds_dwordx4 v[174:175], off
	s_add_u32 s20, s20, 0x10000
	s_addc_u32 s21, s21, 0
	s_mov_b64 s[0:1], 0x1000
	v_lshl_add_u64 v[174:175], v[174:175], 0, s[0:1]

;   DI void gload_k(int t) {
;     const int row0 = rowk0 + t * 64;
;     const u16* kt = Kb + (size_t)row0 * kpitch;
;     const u16* pt = KPEb + (size_t)row0 * 32;
; #pragma unroll
;     for (int q = 0; q < NKL; ++q) {
;       const int c = tid + 256 * q, cc = c % KCH;
;       rk[q] = ldg16(((DQK == 96 && cc >= 8) ? pt : kt) + koff[q]);
;     }
;   }
;   template <int PAR>
;   DI void step(int t, f32x16 (&cur)[2], f32x16 (&nxt)[2]) {
;     ...
;     float psum = 0.f;
; #pragma unroll
;     for (int kb2 = 0; kb2 < 2; ++kb2)
; #pragma unroll
;       for (int i = 0; i < 16; ++i) { const float pv = __builtin_amdgcn_exp2f(cur[kb2][i]); cur[kb2][i] = pv; psum += pv; }
;     l += psum;
;     if (t + 2 < nt) gload_k(t + 2);
.Lm_rareA_ret:
	v_exp_f32_e32 v48, v48
	v_exp_f32_e32 v49, v49
	v_exp_f32_e32 v50, v50
	v_add_f32_e32 v238, v48, v238
	v_exp_f32_e32 v51, v51
	v_add_f32_e32 v239, v49, v239
	v_exp_f32_e32 v52, v52
	v_add_f32_e32 v238, v50, v238
	s_waitcnt lgkmcnt(0)
	v_mfma_f32_32x32x16_bf16 v[80:95], v[96:99], v[136:139], 0
	ds_read_b128 v[96:99], v164 offset:21504
	v_exp_f32_e32 v53, v53
	v_add_f32_e32 v239, v51, v239
	v_exp_f32_e32 v54, v54
	v_add_f32_e32 v238, v52, v238
	v_mfma_f32_32x32x16_bf16 v[64:79], v[100:103], v[136:139], 0
	ds_read_b128 v[100:103], v164 offset:23552
	v_exp_f32_e32 v55, v55
	v_add_f32_e32 v239, v53, v239
	v_cvt_pk_bf16_f32 v48, v48, v49
	v_add_f32_e32 v238, v54, v238
	v_mfma_f32_32x32x16_bf16 v[80:95], v[104:107], v[140:143], v[80:95]
	ds_read_b128 v[104:107], v165 offset:21504
	v_cvt_pk_bf16_f32 v49, v50, v51
	v_add_f32_e32 v239, v55, v239
	v_cvt_pk_bf16_f32 v50, v52, v53
	v_cvt_pk_bf16_f32 v51, v54, v55
	v_mfma_f32_32x32x16_bf16 v[64:79], v[108:111], v[140:143], v[64:79]
	ds_read_b128 v[108:111], v165 offset:23552
	v_exp_f32_e32 v56, v56
	v_exp_f32_e32 v57, v57
	v_exp_f32_e32 v58, v58
	v_add_f32_e32 v238, v56, v238
	s_waitcnt vmcnt(0)
	s_waitcnt lgkmcnt(0)
	s_barrier
	s_add_i32 s0, s31, -1
	s_cmp_ge_u32 s0, s19
	s_cselect_b64 s[14:15], -1, 0
	s_cmp_ge_u32 s31, s19
	s_cbranch_scc1 .Lm_skipKA
	s_add_i32 m0, s44, 13312
	s_nop 0
	global_load_lds_dwordx4 v170, s[20:21]
	global_load_lds_dwordx4 v172, s[20:21] offset:1024
	s_add_i32 m0, s45, 21504
	s_nop 0
	global_load_lds_dwordx4 v[174:175], off
	s_add_u32 s20, s20, 0x10000
	s_addc_u32 s21, s21, 0
	s_mov_b64 s[0:1], 0x1000
	v_lshl_add_u64 v[174:175], v[174:175], 0, s[0:1]

;   DI void gload_k(int t) {
;     const int row0 = rowk0 + t * 64;
;     const u16* kt = Kb + (size_t)row0 * kpitch;
;     const u16* pt = KPEb + (size_t)row0 * 32;
; #pragma unroll
;     for (int q = 0; q < NKL; ++q) {
;       const int c = tid + 256 * q, cc = c % KCH;
;       rk[q] = ldg16(((DQK == 96 && cc >= 8) ? pt : kt) + koff[q]);
;     }
;   }
;   template <int PAR>
;   DI void step(int t, f32x16 (&cur)[2], f32x16 (&nxt)[2]) {
;     ...
;     float psum = 0.f;
; #pragma unroll
;     for (int kb2 = 0; kb2 < 2; ++kb2)
; #pragma unroll
;       for (int i = 0; i < 16; ++i) { const float pv = __builtin_amdgcn_exp2f(cur[kb2][i]); cur[kb2][i] = pv; psum += pv; }
;     l += psum;
;     if (t + 2 < nt) gload_k(t + 2);
.Lm_rareB_ret:
	v_exp_f32_e32 v80, v80
	v_exp_f32_e32 v81, v81
	v_exp_f32_e32 v82, v82
	v_add_f32_e32 v238, v80, v238
	v_exp_f32_e32 v83, v83
	v_add_f32_e32 v239, v81, v239
	v_exp_f32_e32 v84, v84
	v_add_f32_e32 v238, v82, v238
	s_waitcnt lgkmcnt(0)
	v_mfma_f32_32x32x16_bf16 v[48:63], v[96:99], v[136:139], 0
	ds_read_b128 v[96:99], v164 offset:8192
	v_exp_f32_e32 v85, v85
	v_add_f32_e32 v239, v83, v239
	v_exp_f32_e32 v86, v86
	v_add_f32_e32 v238, v84, v238
	v_mfma_f32_32x32x16_bf16 v[32:47], v[100:103], v[136:139], 0
	ds_read_b128 v[100:103], v164 offset:10240
	v_exp_f32_e32 v87, v87
	v_add_f32_e32 v239, v85, v239
	v_cvt_pk_bf16_f32 v80, v80, v81
	v_add_f32_e32 v238, v86, v238
	v_mfma_f32_32x32x16_bf16 v[48:63], v[104:107], v[140:143], v[48:63]
	ds_read_b128 v[104:107], v165 offset:8192
	v_cvt_pk_bf16_f32 v81, v82, v83
	v_add_f32_e32 v239, v87, v239
	v_cvt_pk_bf16_f32 v82, v84, v85
	v_cvt_pk_bf16_f32 v83, v86, v87
	v_mfma_f32_32x32x16_bf16 v[32:47], v[108:111], v[140:143], v[32:47]
	ds_read_b128 v[108:111], v165 offset:10240
	v_exp_f32_e32 v88, v88
	v_exp_f32_e32 v89, v89
	v_exp_f32_e32 v90, v90
	v_add_f32_e32 v238, v88, v238
	s_waitcnt vmcnt(0)
	s_waitcnt lgkmcnt(0)
	s_barrier
	s_add_i32 s0, s31, 1
	s_cmp_ge_u32 s0, s19
	s_cbranch_scc1 .Lm_skipKB
	s_add_i32 m0, s44, 0
	s_nop 0
	global_load_lds_dwordx4 v170, s[20:21]
	global_load_lds_dwordx4 v172, s[20:21] offset:1024
	s_add_i32 m0, s45, 8192
	s_nop 0
	global_load_lds_dwordx4 v[174:175], off
	s_add_u32 s20, s20, 0x10000
	s_addc_u32 s21, s21, 0
	s_mov_b64 s[0:1], 0x1000
	v_lshl_add_u64 v[174:175], v[174:175], 0, s[0:1]
